# kernel entry: the three dependent kernarg SMEM fetches issued together behind one wait
# speedup vs baseline: 1.0048x; 1.0021x over previous
; __global__ void __launch_bounds__(512, 2) mk_fwd(Args args) {
;     ...
;     const int G = gridDim.x, bid = blockIdx.x;
;     unsigned char* ws = args.ws;
;     const float* x = args.in[0]; const float* norm_g = args.in[1]; const float* w_in = args.in[2]; const float* b_gate = args.in[3];
;     const float* lb_logits = args.in[4]; const float* hg_norm_g = args.in[5]; const float* w_sb = args.in[6]; const float* w_hg = args.in[7];
;     const float* w_out = args.in[8]; const float* fng = args.in[9];
;     float* out = args.out;
;     bf16_t* Wt_in = (bf16_t*)(ws + WS_WIN); bf16_t* Wt_sbhg = (bf16_t*)(ws + WS_WSBHG); bf16_t* Wt_out = (bf16_t*)(ws + WS_WOUT);
;     float* DG = (float*)(ws + WS_HGD);
;     bf16_t* Hn = (bf16_t*)(ws + WS_H); bf16_t* SBQ = (bf16_t*)(ws + WS_SBQ); bf16_t* HGQ = (bf16_t*)(ws + WS_HGQ);
;     bf16_t* SBK = (bf16_t*)(ws + WS_SBK); bf16_t* SBV = (bf16_t*)(ws + WS_SBV); bf16_t* HGI = (bf16_t*)(ws + WS_HGI);
;     float* ST = (float*)(ws + WS_ST); bf16_t* GATES = (bf16_t*)(ws + WS_GATES); bf16_t* Y = (bf16_t*)(ws + WS_Y);
;     float* Gf = out;
;     const int lo = args.ph_lo, hi = args.ph_hi;
_Z6mk_fwd4Args:
	v_mov_b32_e32 v251, 0
	s_mov_b32 s99, 0
	s_load_dwordx4 s[68:71], s[0:1], 0x60
	s_load_dword s3, s[0:1], 0x70
	s_load_dwordx8 s[60:67], s[0:1], 0x40
	s_load_dwordx16 s[76:91], s[0:1], 0x0
	s_add_u32 s6, s0, 0x68
	s_addc_u32 s7, s1, 0
	v_and_b32_e32 v200, 0x3ff, v0
	s_waitcnt lgkmcnt(0)
	s_cmp_gt_i32 s68, -1
	v_writelane_b32 v250, s3, 0
	s_movk_i32 s3, 0x3ff
	s_cbranch_scc0 .LBB0_26
	v_cmp_gt_u32_e32 vcc, 16, v200
	s_and_saveexec_b64 s[4:5], vcc

; #define LAS __attribute__((address_space(3)))
; __device__ __forceinline__ unsigned xb_add(unsigned* p, unsigned v) { return __hip_atomic_fetch_add(p, v, __ATOMIC_RELAXED, __HIP_MEMORY_SCOPE_AGENT); }
; __device__ __forceinline__ unsigned xb_xcc_id() { return (unsigned)__builtin_amdgcn_s_getreg((3 << 11) | 20) & 0xFu; }
; __device__ __forceinline__ XcdBarrier xcd_barrier_post(unsigned* bar, volatile LAS unsigned* st) {
;     XcdBarrier b; b.bar = bar; b.x = xb_xcc_id(); b.st = st;
;     if (threadIdx.x == 0) (void)xb_add(&bar[XB_XCNT(b.x)], 1u);
;     return b;
; }
; __global__ void __launch_bounds__(512, 2) mk_fwd(Args args) {
;     ...
;     if (tid < 16) ((LAS unsigned*)(lds + LDS_MISC))[tid] = 0u;
;     __syncthreads();
;     XcdBarrier bar = xcd_barrier_post((unsigned*)ws, (volatile LAS unsigned*)(lds + LDS_MISC));
.LBB0_3:
	s_or_b64 exec, exec, s[4:5]
	s_mov_b64 s[4:5], s[76:77]
	s_mov_b64 s[6:7], s[78:79]
	s_mov_b64 s[8:9], s[80:81]
	s_mov_b64 s[10:11], s[82:83]
	s_mov_b64 s[12:13], s[84:85]
	s_mov_b64 s[14:15], s[86:87]
	s_mov_b64 s[16:17], s[88:89]
	s_mov_b64 s[18:19], s[90:91]
	s_waitcnt lgkmcnt(0)
	s_barrier
	s_getreg_b32 s0, hwreg(HW_REG_XCC_ID, 0, 4)
	v_writelane_b32 v250, s4, 1
	s_and_b32 s46, s0, 15
	v_cmp_eq_u32_e64 s[92:93], 0, v200
	v_writelane_b32 v250, s5, 2
	v_writelane_b32 v250, s6, 3
	v_writelane_b32 v250, s7, 4
	v_writelane_b32 v250, s8, 5
	v_writelane_b32 v250, s9, 6
	v_writelane_b32 v250, s10, 7
	v_writelane_b32 v250, s11, 8
	v_writelane_b32 v250, s12, 9
	v_writelane_b32 v250, s13, 10
	v_writelane_b32 v250, s14, 11
	v_writelane_b32 v250, s15, 12
	v_writelane_b32 v250, s16, 13
	v_writelane_b32 v250, s17, 14
	v_writelane_b32 v250, s18, 15
	v_writelane_b32 v250, s19, 16
	s_and_saveexec_b64 s[4:5], s[92:93]
	s_cbranch_execz .LBB0_6
	s_mov_b64 s[6:7], exec
	v_mbcnt_lo_u32_b32 v0, s6, 0
	v_mbcnt_hi_u32_b32 v0, s7, v0
	v_cmp_eq_u32_e32 vcc, 0, v0
	s_and_b64 s[0:1], exec, vcc
	s_mov_b64 exec, s[0:1]
	s_cbranch_execz .LBB0_6
	s_lshl_b32 s0, s46, 8
	s_bcnt1_i32_b64 s1, s[6:7]
	v_mov_b32_e32 v0, s0
	v_mov_b32_e32 v1, s1
	global_atomic_add v0, v1, s[66:67] offset:1024
